# cross-half softmax row-max exchange via v_permlane32_swap instead of ds_bpermute + lgkmcnt wait in the five attention loops
# baseline (speedup 1.0000x reference)
; #define LAS __attribute__((address_space(3)))
; #define MFMA32(a, b, c) __builtin_amdgcn_mfma_f32_32x32x16_bf16((a), (b), (c), 0, 0, 0)
; template <int DQK, int VAR> __device__ __forceinline__ void att_tile(LAS unsigned char* lds, int kt, int mylast, int grp, bool& pend, int vs_prev, int vs_cur, int lane_off, int r, int h, ...
;     ...
;     if (kt <= mylast) {
;         f32x16 S0, S1;
; #pragma unroll
;         for (int i = 0; i < 16; ++i) { S0[i] = 0.f; S1[i] = 0.f; }
;         const LAS unsigned char* kb = lds + (kt & 1) * ATT_KBYTES + r * KP + h * 16;
;         bf16x8 ka[3][2];
;         ka[0][0] = *(const LAS bf16x8*)(kb); ka[0][1] = *(const LAS bf16x8*)(kb + 32 * KP);
;         ka[1][0] = *(const LAS bf16x8*)(kb + 32); ka[1][1] = *(const LAS bf16x8*)(kb + 32 * KP + 32);
; #pragma unroll
;         for (int s = 0; s < NS; ++s) {
;             if (s + 2 < NS) { ka[(s + 2) % 3][0] = *(const LAS bf16x8*)(kb + (s + 2) * 32); ka[(s + 2) % 3][1] = *(const LAS bf16x8*)(kb + 32 * KP + (s + 2) * 32); }
;             if (VAR == 4) { S0[s & 15] += __builtin_bit_cast(f32x4, ka[s % 3][0])[0] * __builtin_bit_cast(f32x4, qf[s])[1]; S1[s & 15] += __builtin_bit_cast(f32x4, ka[s % 3][1])[2]; }
;             else { S0 = MFMA32(ka[s % 3][0], qf[s], S0); S1 = MFMA32(ka[s % 3][1], qf[s], S1); }
;             __builtin_amdgcn_sched_barrier(0);
;         }
;         if (VAR != 5) {
;         float mx = S0[0];
; #pragma unroll
;         for (int i = 1; i < 16; ++i) mx = fmaxf(mx, S0[i]);
; #pragma unroll
;         for (int i = 0; i < 16; ++i) mx = fmaxf(mx, S1[i]);
;         mx = fmaxf(mx, __shfl_xor(mx, 32));
;         const float mn = fmaxf(mrun, mx), alpha = __builtin_amdgcn_exp2f(mrun - mn);
;         const bool grew = __builtin_amdgcn_ballot_w64(mn > mrun) != 0ull;
;         mrun = mn;
;         float ps = 0.f;
; #pragma unroll
;         for (int i = 0; i < 16; ++i) { S0[i] = (VAR == 2) ? (S0[i] - mn) : __builtin_amdgcn_exp2f(S0[i] - mn); ps += S0[i]; }
; #pragma unroll
;         for (int i = 0; i < 16; ++i) { S1[i] = (VAR == 2) ? (S1[i] - mn) : __builtin_amdgcn_exp2f(S1[i] - mn); ps += S1[i]; }
;         lrun = lrun * alpha + ps;
;         if (grew) {
; #pragma unroll
;             for (int db = 0; db < 4; ++db) O[db] = O[db] * alpha;
.LBB0_769:
	s_cmp_gt_i32 s27, s69
	s_cbranch_scc1 .LBB0_773
	s_bitcmp1_b32 s27, 0
	s_cselect_b32 s26, 0x6400, 0
	v_add_u32_e32 v0, s26, v191
	ds_read_b128 v[66:69], v0
	ds_read_b128 v[196:199], v0 offset:32
	s_waitcnt lgkmcnt(1)
	v_mfma_f32_32x32x16_bf16 v[82:97], v[66:69], v[98:101], 0
	ds_read_b128 v[66:69], v0 offset:12800
	ds_read_b128 v[212:215], v0 offset:64
	ds_read_b128 v[216:219], v0 offset:12832
	ds_read_b128 v[220:223], v0 offset:12864
	s_waitcnt lgkmcnt(3)
	v_mfma_f32_32x32x16_bf16 v[66:81], v[66:69], v[98:101], 0
	v_mfma_f32_32x32x16_bf16 v[82:97], v[196:199], v[102:105], v[82:97]
	ds_read_b128 v[196:199], v0 offset:96
	ds_read_b128 v[230:233], v0 offset:12896
	s_waitcnt lgkmcnt(3)
	v_mfma_f32_32x32x16_bf16 v[66:81], v[216:219], v[102:105], v[66:81]
	v_mfma_f32_32x32x16_bf16 v[82:97], v[212:215], v[106:109], v[82:97]
	ds_read_b128 v[212:215], v0 offset:128
	ds_read_b128 v[216:219], v0 offset:12928
	s_waitcnt lgkmcnt(4)
	v_mfma_f32_32x32x16_bf16 v[66:81], v[220:223], v[106:109], v[66:81]
	s_waitcnt lgkmcnt(3)
	v_mfma_f32_32x32x16_bf16 v[82:97], v[196:199], v[110:113], v[82:97]
	ds_read_b128 v[196:199], v0 offset:160
	ds_read_b128 v[220:223], v0 offset:12960
	s_waitcnt lgkmcnt(4)
	v_mfma_f32_32x32x16_bf16 v[66:81], v[230:233], v[110:113], v[66:81]
	s_waitcnt lgkmcnt(3)
	v_mfma_f32_32x32x16_bf16 v[82:97], v[212:215], v[114:117], v[82:97]
	ds_read_b128 v[212:215], v0 offset:192
	ds_read_b128 v[230:233], v0 offset:12992
	s_waitcnt lgkmcnt(4)
	v_mfma_f32_32x32x16_bf16 v[66:81], v[216:219], v[114:117], v[66:81]
	s_waitcnt lgkmcnt(3)
	v_mfma_f32_32x32x16_bf16 v[82:97], v[196:199], v[118:121], v[82:97]
	ds_read_b128 v[196:199], v0 offset:224
	ds_read_b128 v[216:219], v0 offset:13024
	s_waitcnt lgkmcnt(4)
	v_mfma_f32_32x32x16_bf16 v[66:81], v[220:223], v[118:121], v[66:81]
	s_waitcnt lgkmcnt(3)
	v_mfma_f32_32x32x16_bf16 v[82:97], v[212:215], v[122:125], v[82:97]
	ds_read_b128 v[212:215], v0 offset:256
	ds_read_b128 v[220:223], v0 offset:13056
	s_waitcnt lgkmcnt(4)
	v_mfma_f32_32x32x16_bf16 v[66:81], v[230:233], v[122:125], v[66:81]
	s_waitcnt lgkmcnt(3)
	v_mfma_f32_32x32x16_bf16 v[82:97], v[196:199], v[126:129], v[82:97]
	ds_read_b128 v[196:199], v0 offset:288
	ds_read_b128 v[230:233], v0 offset:13088
	s_waitcnt lgkmcnt(4)
	v_mfma_f32_32x32x16_bf16 v[66:81], v[216:219], v[126:129], v[66:81]
	s_waitcnt lgkmcnt(3)
	v_mfma_f32_32x32x16_bf16 v[82:97], v[212:215], v[130:133], v[82:97]
	ds_read_b128 v[212:215], v0 offset:320
	ds_read_b128 v[216:219], v0 offset:13120
	s_waitcnt lgkmcnt(4)
	v_mfma_f32_32x32x16_bf16 v[66:81], v[220:223], v[130:133], v[66:81]
	s_waitcnt lgkmcnt(3)
	v_mfma_f32_32x32x16_bf16 v[82:97], v[196:199], v[134:137], v[82:97]
	ds_read_b128 v[196:199], v0 offset:352
	ds_read_b128 v[220:223], v0 offset:13152
	s_waitcnt lgkmcnt(4)
	v_mfma_f32_32x32x16_bf16 v[66:81], v[230:233], v[134:137], v[66:81]
	s_waitcnt lgkmcnt(3)
	v_mfma_f32_32x32x16_bf16 v[82:97], v[212:215], v[138:141], v[82:97]
	s_waitcnt lgkmcnt(2)
	v_mfma_f32_32x32x16_bf16 v[66:81], v[216:219], v[138:141], v[66:81]
	s_waitcnt lgkmcnt(1)
	v_mfma_f32_32x32x16_bf16 v[82:97], v[196:199], v[142:145], v[82:97]
	s_nop 11
	v_max_f32_e32 v0, v83, v83
	v_max_f32_e32 v193, v82, v82
	v_max_f32_e32 v0, v193, v0
	s_waitcnt lgkmcnt(0)
	v_mfma_f32_32x32x16_bf16 v[66:81], v[220:223], v[142:145], v[66:81]
	v_max3_f32 v0, v0, v84, v85
	v_max3_f32 v0, v0, v86, v87
	v_max3_f32 v0, v0, v88, v89
	v_max3_f32 v0, v0, v90, v91
	v_max3_f32 v0, v0, v92, v93
	v_max3_f32 v0, v0, v94, v95
	v_max3_f32 v0, v0, v96, v97
	s_nop 4
	v_max3_f32 v0, v0, v66, v67
	v_max3_f32 v0, v0, v68, v69
	v_max3_f32 v0, v0, v70, v71
	v_max3_f32 v0, v0, v72, v73
	v_max3_f32 v0, v0, v74, v75
	v_max3_f32 v0, v0, v76, v77
	v_max3_f32 v0, v0, v78, v79
	v_max3_f32 v0, v0, v80, v81
	v_mov_b32_e32 v193, v0
	s_nop 1
	v_permlane32_swap_b32_e32 v193, v0
	s_waitcnt lgkmcnt(0)
	v_max3_f32 v193, v194, v0, v193
	v_sub_f32_e32 v0, v193, v194
	v_cmp_lt_f32_e32 vcc, 4.0, v0
	v_cndmask_b32_e32 v193, v194, v193, vcc
	v_sub_f32_e32 v0, v194, v193
	v_exp_f32_e32 v0, v0
	v_cmp_gt_f32_e32 vcc, v193, v194
	s_cbranch_vccz .LBB0_772
	v_pk_mul_f32 v[16:17], v[16:17], v[0:1] op_sel_hi:[1,0]
	v_pk_mul_f32 v[14:15], v[14:15], v[0:1] op_sel_hi:[1,0]
	v_pk_mul_f32 v[12:13], v[12:13], v[0:1] op_sel_hi:[1,0]
	v_pk_mul_f32 v[10:11], v[10:11], v[0:1] op_sel_hi:[1,0]
	v_pk_mul_f32 v[8:9], v[8:9], v[0:1] op_sel_hi:[1,0]
	v_pk_mul_f32 v[6:7], v[6:7], v[0:1] op_sel_hi:[1,0]
	v_pk_mul_f32 v[4:5], v[4:5], v[0:1] op_sel_hi:[1,0]
	v_pk_mul_f32 v[2:3], v[2:3], v[0:1] op_sel_hi:[1,0]
	v_pk_mul_f32 v[32:33], v[32:33], v[0:1] op_sel_hi:[1,0]
	v_pk_mul_f32 v[30:31], v[30:31], v[0:1] op_sel_hi:[1,0]
	v_pk_mul_f32 v[28:29], v[28:29], v[0:1] op_sel_hi:[1,0]
	v_pk_mul_f32 v[26:27], v[26:27], v[0:1] op_sel_hi:[1,0]
	v_pk_mul_f32 v[24:25], v[24:25], v[0:1] op_sel_hi:[1,0]
	v_pk_mul_f32 v[22:23], v[22:23], v[0:1] op_sel_hi:[1,0]
	v_pk_mul_f32 v[20:21], v[20:21], v[0:1] op_sel_hi:[1,0]
	v_pk_mul_f32 v[18:19], v[18:19], v[0:1] op_sel_hi:[1,0]
	v_pk_mul_f32 v[48:49], v[48:49], v[0:1] op_sel_hi:[1,0]
	v_pk_mul_f32 v[46:47], v[46:47], v[0:1] op_sel_hi:[1,0]
	v_pk_mul_f32 v[44:45], v[44:45], v[0:1] op_sel_hi:[1,0]
	v_pk_mul_f32 v[42:43], v[42:43], v[0:1] op_sel_hi:[1,0]
	v_pk_mul_f32 v[40:41], v[40:41], v[0:1] op_sel_hi:[1,0]
	v_pk_mul_f32 v[38:39], v[38:39], v[0:1] op_sel_hi:[1,0]
	v_pk_mul_f32 v[36:37], v[36:37], v[0:1] op_sel_hi:[1,0]
	v_pk_mul_f32 v[34:35], v[34:35], v[0:1] op_sel_hi:[1,0]
	v_pk_mul_f32 v[64:65], v[64:65], v[0:1] op_sel_hi:[1,0]
	v_pk_mul_f32 v[62:63], v[62:63], v[0:1] op_sel_hi:[1,0]
	v_pk_mul_f32 v[60:61], v[60:61], v[0:1] op_sel_hi:[1,0]
	v_pk_mul_f32 v[58:59], v[58:59], v[0:1] op_sel_hi:[1,0]
	v_pk_mul_f32 v[56:57], v[56:57], v[0:1] op_sel_hi:[1,0]
	v_pk_mul_f32 v[54:55], v[54:55], v[0:1] op_sel_hi:[1,0]
	v_pk_mul_f32 v[52:53], v[52:53], v[0:1] op_sel_hi:[1,0]
	v_pk_mul_f32 v[50:51], v[50:51], v[0:1] op_sel_hi:[1,0]

; #define LAS __attribute__((address_space(3)))
; #define MFMA32(a, b, c) __builtin_amdgcn_mfma_f32_32x32x16_bf16((a), (b), (c), 0, 0, 0)
; template <int DQK, int VAR> __device__ __forceinline__ void att_tile_fused(LAS unsigned char* lds, int kt, int mylast, bool& pend, int vs_prev, int vs_cur, int lane_off, int r, int h, ...
;     ...
;     f32x16 S0, S1;
; #pragma unroll
;     for (int i = 0; i < 16; ++i) { S0[i] = 0.f; S1[i] = 0.f; }
;     const LAS unsigned char* kb = lds + (kt & 1) * ATT_KBYTES + r * KP + h * 16;
;     bf16x8 ka[2][2];
;     ka[0][0] = *(const LAS bf16x8*)(kb); ka[0][1] = *(const LAS bf16x8*)(kb + 32 * KP);
; #pragma unroll
;     for (int s = 0; s < NS; ++s) {
;         if (s + 1 < NS) { ka[(s + 1) & 1][0] = *(const LAS bf16x8*)(kb + (s + 1) * 32); ka[(s + 1) & 1][1] = *(const LAS bf16x8*)(kb + 32 * KP + (s + 1) * 32); }
;         S0 = MFMA32(ka[s & 1][0], qf[s], S0); S1 = MFMA32(ka[s & 1][1], qf[s], S1);
;         __builtin_amdgcn_sched_barrier(0);
;     }
;     const LAS unsigned char* vb = lds + ATT_VOFF + (pend ? vs_prev : vs_cur) * ATT_VBYTES + lane_off;
;     bf16x8 va[2][4];
; #pragma unroll
;     for (int js = 0; js < 4; ++js) va[0][js] = *(const LAS bf16x8*)(vb + js * 32);
;     float mx = S0[0];
; #pragma unroll
;     for (int i = 1; i < 16; ++i) mx = fmaxf(mx, S0[i]);
; #pragma unroll
;     for (int i = 0; i < 16; ++i) mx = fmaxf(mx, S1[i]);
;     mx = fmaxf(mx, __shfl_xor(mx, 32));
;     const float mn = fmaxf(mrun, mx), alpha = __builtin_amdgcn_exp2f(mrun - mn);
;     const bool grew = __builtin_amdgcn_ballot_w64(mn > mrun) != 0ull;
;     mrun = mn;
;     float ps = 0.f;
;     u32x4 w0, w1, w2, w3;
;     __builtin_amdgcn_sched_barrier(0);
; #pragma unroll
;     for (int db = 0; db < 4; ++db) {
;         if (db < 3) {
; #pragma unroll
;             for (int js = 0; js < 4; ++js) va[(db + 1) & 1][js] = *(const LAS bf16x8*)(vb + (db + 1) * 32 * VPB + js * 32);
;         }
; #pragma unroll
;         for (int js = 0; js < 4; ++js) {
;             const int c = db * 4 + js;
;             O[db] = MFMA32(va[db & 1][js], pf[js], O[db]);
;             S0[c] = __builtin_amdgcn_exp2f(S0[c] - mn); S1[c] = __builtin_amdgcn_exp2f(S1[c] - mn); ps += S0[c] + S1[c];
.LBB0_799:
	s_andn2_b64 vcc, exec, s[36:37]
	s_mov_b64 s[36:37], 0
	s_cbranch_vccnz .LBB0_801
	v_add_u32_e32 v0, v230, v212
	ds_read_b128 v[2:5], v0
	ds_read_b128 v[6:9], v0 offset:32
	s_waitcnt lgkmcnt(1)
	v_mfma_f32_32x32x16_bf16 v[80:95], v[2:5], v[144:147], 0
	ds_read_b128 v[2:5], v0 offset:4608
	ds_read_b128 v[10:13], v0 offset:4640
	s_waitcnt lgkmcnt(1)
	v_mfma_f32_32x32x16_bf16 v[96:111], v[2:5], v[144:147], 0
	v_mfma_f32_32x32x16_bf16 v[80:95], v[6:9], v[156:159], v[80:95]
	ds_read_b128 v[2:5], v0 offset:64
	ds_read_b128 v[6:9], v0 offset:4672
	s_waitcnt lgkmcnt(2)
	v_mfma_f32_32x32x16_bf16 v[96:111], v[10:13], v[156:159], v[96:111]
	s_waitcnt lgkmcnt(1)
	v_mfma_f32_32x32x16_bf16 v[80:95], v[2:5], v[160:163], v[80:95]
	ds_read_b128 v[2:5], v0 offset:96
	ds_read_b128 v[10:13], v0 offset:4704
	s_waitcnt lgkmcnt(2)
	v_mfma_f32_32x32x16_bf16 v[96:111], v[6:9], v[160:163], v[96:111]
	s_waitcnt lgkmcnt(1)
	v_mfma_f32_32x32x16_bf16 v[80:95], v[2:5], v[168:171], v[80:95]
	s_and_b64 s[34:35], s[34:35], exec
	s_cselect_b32 s14, s27, s74
	s_mulk_i32 s14, 0x4800
	v_add_u32_e32 v132, s14, v233
	s_waitcnt lgkmcnt(0)
	v_mfma_f32_32x32x16_bf16 v[96:111], v[10:13], v[168:171], v[96:111]
	s_nop 5
	v_max_f32_e32 v0, v81, v81
	v_max_f32_e32 v2, v80, v80
	v_max_f32_e32 v0, v2, v0
	v_max3_f32 v0, v0, v82, v83
	v_max3_f32 v0, v0, v84, v85
	v_max3_f32 v0, v0, v86, v87
	v_max3_f32 v0, v0, v88, v89
	v_max3_f32 v0, v0, v90, v91
	v_max3_f32 v0, v0, v92, v93
	v_max3_f32 v0, v0, v94, v95
	v_max3_f32 v0, v0, v96, v97
	v_max3_f32 v0, v0, v98, v99
	v_max3_f32 v0, v0, v100, v101
	v_max3_f32 v0, v0, v102, v103
	v_max3_f32 v0, v0, v104, v105
	v_max3_f32 v0, v0, v106, v107
	v_max3_f32 v0, v0, v108, v109
	v_max3_f32 v0, v0, v110, v111
	v_mov_b32_e32 v14, v0
	s_nop 1
	v_permlane32_swap_b32_e32 v14, v0
	ds_read_b128 v[2:5], v132 offset:51200
	ds_read_b128 v[6:9], v132 offset:51232
	ds_read_b128 v[10:13], v132 offset:51264
	ds_read_b128 v[112:115], v132 offset:51296
	s_waitcnt lgkmcnt(4)
	v_max3_f32 v236, v235, v0, v14
	v_sub_f32_e32 v133, v236, v235
	v_cmp_lt_f32_e32 vcc, 4.0, v133
	v_cndmask_b32_e32 v236, v235, v236, vcc
	v_cmp_gt_f32_e32 vcc, v236, v235
	s_cmp_lg_u64 vcc, 0
	v_sub_f32_e32 v133, v235, v236
	s_cselect_b64 s[36:37], -1, 0
	ds_read_b128 v[116:119], v132 offset:55808
	ds_read_b128 v[120:123], v132 offset:55840
	ds_read_b128 v[124:127], v132 offset:55872
	ds_read_b128 v[128:131], v132 offset:55904
	v_sub_f32_e32 v0, v80, v236
	v_exp_f32_e32 v14, v0
	v_sub_f32_e32 v0, v96, v236
	v_exp_f32_e32 v15, v0
	s_waitcnt lgkmcnt(7)
	v_mfma_f32_32x32x16_bf16 v[32:47], v[2:5], v[164:167], v[32:47]
	v_add_f32_e32 v3, v15, v14
	v_sub_f32_e32 v0, v81, v236
	v_sub_f32_e32 v2, v97, v236
	v_exp_f32_e32 v0, v0
	v_exp_f32_e32 v2, v2
	s_waitcnt lgkmcnt(6)
	v_mfma_f32_32x32x16_bf16 v[32:47], v[6:9], v[148:151], v[32:47]
	v_add_f32_e64 v4, v2, v0
	v_add_f32_e64 v5, v3, v1
	v_add_f32_e32 v5, v4, v5
	v_cvt_pk_bf16_f32 v237, v15, v2
	v_cvt_pk_bf16_f32 v0, v14, v0
	v_sub_f32_e32 v2, v82, v236
	v_exp_f32_e32 v8, v2
	v_sub_f32_e32 v2, v98, v236
	v_exp_f32_e32 v9, v2
	s_waitcnt lgkmcnt(5)
	v_mfma_f32_32x32x16_bf16 v[32:47], v[10:13], v[172:175], v[32:47]
	v_add_f32_e32 v3, v9, v8
	v_sub_f32_e32 v2, v83, v236
	v_exp_f32_e32 v4, v2
	v_sub_f32_e32 v2, v99, v236
	v_exp_f32_e32 v2, v2
	s_waitcnt lgkmcnt(4)
	v_mfma_f32_32x32x16_bf16 v[32:47], v[112:115], v[152:155], v[32:47]
	v_cvt_pk_bf16_f32 v238, v8, v4
	v_add_f32_e64 v6, v2, v4
	v_add_f32_e64 v7, v3, v5
	v_add_f32_e64 v14, v6, v6
	v_add_f32_e64 v15, v6, v7
	v_cvt_pk_bf16_f32 v239, v9, v2
	ds_read_b128 v[2:5], v132 offset:60416
	ds_read_b128 v[6:9], v132 offset:60448
	ds_read_b128 v[10:13], v132 offset:60480
	ds_read_b128 v[80:83], v132 offset:60512
	v_sub_f32_e32 v14, v84, v236
	v_exp_f32_e32 v98, v14
	v_sub_f32_e32 v14, v100, v236
	v_exp_f32_e32 v99, v14
	s_waitcnt lgkmcnt(7)
	v_mfma_f32_32x32x16_bf16 v[64:79], v[116:119], v[164:167], v[64:79]
	v_add_f32_e32 v97, v99, v98
	v_sub_f32_e32 v14, v85, v236
	v_sub_f32_e32 v84, v101, v236
	v_exp_f32_e32 v14, v14
	v_exp_f32_e32 v96, v84
	s_waitcnt lgkmcnt(6)
	v_mfma_f32_32x32x16_bf16 v[64:79], v[120:123], v[148:151], v[64:79]
	v_cvt_pk_bf16_f32 v240, v98, v14
	v_add_f32_e64 v84, v96, v14
	v_add_f32_e64 v85, v97, v15
	v_cvt_pk_bf16_f32 v241, v99, v96
	v_add_f32_e32 v85, v84, v85
	v_sub_f32_e32 v14, v86, v236
	v_exp_f32_e32 v96, v14
	v_sub_f32_e32 v14, v102, v236
	v_exp_f32_e32 v97, v14
	s_waitcnt lgkmcnt(5)
; #define LAS __attribute__((address_space(3)))
; __device__ __forceinline__ unsigned pk2(float lo, float hi) { f32x2_t v = {lo, hi}; bf16x2_t b = __builtin_convertvector(v, bf16x2_t); return __builtin_bit_cast(unsigned, b); }
; #define MFMA32(a, b, c) __builtin_amdgcn_mfma_f32_32x32x16_bf16((a), (b), (c), 0, 0, 0)
; template <int DQK, int VAR> __device__ __forceinline__ void att_tile_fused(LAS unsigned char* lds, int kt, int mylast, bool& pend, int vs_prev, int vs_cur, int lane_off, int r, int h, ...
;     ...
; #pragma unroll
;     for (int db = 0; db < 4; ++db) {
;         if (db < 3) {
; #pragma unroll
;             for (int js = 0; js < 4; ++js) va[(db + 1) & 1][js] = *(const LAS bf16x8*)(vb + (db + 1) * 32 * VPB + js * 32);
;         }
; #pragma unroll
;         for (int js = 0; js < 4; ++js) {
;             const int c = db * 4 + js;
;             O[db] = MFMA32(va[db & 1][js], pf[js], O[db]);
;             S0[c] = __builtin_amdgcn_exp2f(S0[c] - mn); S1[c] = __builtin_amdgcn_exp2f(S1[c] - mn); ps += S0[c] + S1[c];
;             if (c & 1) {
;                 const unsigned a = pk2(S0[c - 1], S0[c]), b = pk2(S1[c - 1], S1[c]);
;                 const int q = c >> 1;
;                 if (q == 0) { w0.x = a; w2.x = b; } else if (q == 1) { w0.y = a; w2.y = b; } else if (q == 2) { w0.z = a; w2.z = b; } else if (q == 3) { w0.w = a; w2.w = b; }
;                 else if (q == 4) { w1.x = a; w3.x = b; } else if (q == 5) { w1.y = a; w3.y = b; } else if (q == 6) { w1.z = a; w3.z = b; } else { w1.w = a; w3.w = b; }
;             }
;             __builtin_amdgcn_sched_barrier(0);
;         }
;     }
;     lrun = lrun * alpha + ps;
;     alpha_p = alpha; grew_p = grew;
;     pf[0] = __builtin_bit_cast(bf16x8, w0); pf[1] = __builtin_bit_cast(bf16x8, w1); pf[2] = __builtin_bit_cast(bf16x8, w2); pf[3] = __builtin_bit_cast(bf16x8, w3);
	v_mfma_f32_32x32x16_bf16 v[64:79], v[124:127], v[172:175], v[64:79]
	v_add_f32_e32 v15, v97, v96
	v_sub_f32_e32 v14, v87, v236
	v_exp_f32_e32 v84, v14
	v_sub_f32_e32 v14, v103, v236
	v_exp_f32_e32 v14, v14
	s_waitcnt lgkmcnt(4)
	v_mfma_f32_32x32x16_bf16 v[64:79], v[128:131], v[152:155], v[64:79]
	v_add_f32_e64 v86, v14, v84
	v_add_f32_e64 v87, v15, v85
	v_add_f32_e64 v116, v86, v86
	v_add_f32_e64 v117, v86, v87
	v_cvt_pk_bf16_f32 v15, v96, v84
	v_cvt_pk_bf16_f32 v14, v97, v14
	ds_read_b128 v[84:87], v132 offset:65024
	ds_read_b128 v[96:99], v132 offset:65056
	ds_read_b128 v[100:103], v132 offset:65088
	ds_read_b128 v[112:115], v132 offset:65120
	v_sub_f32_e32 v88, v88, v236
	v_sub_f32_e32 v104, v104, v236
	v_exp_f32_e32 v88, v88
	v_exp_f32_e32 v104, v104
	s_waitcnt lgkmcnt(7)
	v_mfma_f32_32x32x16_bf16 v[48:63], v[2:5], v[164:167], v[48:63]
	v_add_f32_e32 v3, v104, v88
	v_sub_f32_e32 v2, v89, v236
	v_exp_f32_e32 v116, v2
	v_sub_f32_e32 v2, v105, v236
	v_exp_f32_e32 v2, v2
	s_waitcnt lgkmcnt(6)
	v_mfma_f32_32x32x16_bf16 v[48:63], v[6:9], v[148:151], v[48:63]
	v_cvt_pk_bf16_f32 v8, v88, v116
	v_add_f32_e64 v4, v2, v116
	v_add_f32_e64 v5, v3, v117
	v_add_f32_e32 v5, v4, v5
	v_cvt_pk_bf16_f32 v9, v104, v2
	v_sub_f32_e32 v2, v90, v236
	v_exp_f32_e32 v88, v2
	v_sub_f32_e32 v2, v106, v236
	v_exp_f32_e32 v89, v2
	s_waitcnt lgkmcnt(5)
	v_mfma_f32_32x32x16_bf16 v[48:63], v[10:13], v[172:175], v[48:63]
	v_add_f32_e32 v3, v89, v88
	v_sub_f32_e32 v2, v91, v236
	v_exp_f32_e32 v4, v2
	v_sub_f32_e32 v2, v107, v236
	v_exp_f32_e32 v2, v2
	s_waitcnt lgkmcnt(4)
	v_mfma_f32_32x32x16_bf16 v[48:63], v[80:83], v[152:155], v[48:63]
	v_cvt_pk_bf16_f32 v10, v88, v4
	v_add_f32_e64 v6, v2, v4
	v_add_f32_e64 v7, v3, v5
	v_add_f32_e32 v7, v6, v7
	v_cvt_pk_bf16_f32 v11, v89, v2
	v_sub_f32_e32 v2, v92, v236
	v_exp_f32_e32 v12, v2
	v_sub_f32_e32 v2, v108, v236
	v_exp_f32_e32 v13, v2
	s_waitcnt lgkmcnt(3)
	v_mfma_f32_32x32x16_bf16 v[16:31], v[84:87], v[164:167], v[16:31]
	v_add_f32_e32 v3, v13, v12
	v_sub_f32_e32 v2, v93, v236
	v_exp_f32_e32 v6, v2
	v_sub_f32_e32 v2, v109, v236
	v_exp_f32_e32 v2, v2
	s_waitcnt lgkmcnt(2)
	v_mfma_f32_32x32x16_bf16 v[16:31], v[96:99], v[148:151], v[16:31]
	v_cvt_pk_bf16_f32 v150, v12, v6
	v_add_f32_e64 v4, v2, v6
	v_add_f32_e64 v5, v3, v7
	v_add_f32_e32 v5, v4, v5
	v_cvt_pk_bf16_f32 v12, v13, v2
	v_sub_f32_e32 v2, v94, v236
	v_exp_f32_e32 v13, v2
	v_sub_f32_e32 v2, v110, v236
	v_exp_f32_e32 v80, v2
	s_waitcnt lgkmcnt(1)
	v_mfma_f32_32x32x16_bf16 v[16:31], v[100:103], v[172:175], v[16:31]
	v_add_f32_e32 v3, v80, v13
	v_sub_f32_e32 v2, v95, v236
	v_exp_f32_e32 v4, v2
	v_sub_f32_e32 v2, v111, v236
	v_exp_f32_e32 v2, v2
	s_waitcnt lgkmcnt(0)
	v_mfma_f32_32x32x16_bf16 v[16:31], v[112:115], v[152:155], v[16:31]
	v_cvt_pk_bf16_f32 v151, v13, v4
	v_add_f32_e64 v6, v2, v4
	v_add_f32_e64 v7, v3, v5
	v_cvt_pk_bf16_f32 v155, v80, v2
	v_add_f32_e32 v3, v6, v7
	v_exp_f32_e32 v224, v133
	s_nop 5
	v_mov_b64_e32 v[142:143], v[30:31]
	v_mov_b64_e32 v[126:127], v[62:63]
	v_mov_b64_e32 v[110:111], v[78:79]
	v_fmac_f32_e32 v3, v211, v224
	v_mov_b64_e32 v[94:95], v[46:47]
	v_mov_b64_e32 v[140:141], v[28:29]
	v_mov_b64_e32 v[138:139], v[26:27]
	v_mov_b64_e32 v[136:137], v[24:25]
	v_mov_b64_e32 v[134:135], v[22:23]
	v_mov_b64_e32 v[132:133], v[20:21]
	v_mov_b64_e32 v[130:131], v[18:19]
	v_mov_b64_e32 v[128:129], v[16:17]
	v_mov_b64_e32 v[124:125], v[60:61]
	v_mov_b64_e32 v[122:123], v[58:59]
	v_mov_b64_e32 v[120:121], v[56:57]
	v_mov_b64_e32 v[118:119], v[54:55]
	v_mov_b64_e32 v[116:117], v[52:53]
	v_mov_b64_e32 v[114:115], v[50:51]
	v_mov_b64_e32 v[112:113], v[48:49]
	v_mov_b64_e32 v[108:109], v[76:77]
	v_mov_b64_e32 v[106:107], v[74:75]
	v_mov_b64_e32 v[104:105], v[72:73]
	v_mov_b64_e32 v[102:103], v[70:71]
	v_mov_b64_e32 v[100:101], v[68:69]
	v_mov_b64_e32 v[98:99], v[66:67]
	v_mov_b64_e32 v[96:97], v[64:65]
	v_mov_b64_e32 v[92:93], v[44:45]
	v_mov_b64_e32 v[90:91], v[42:43]
	v_mov_b64_e32 v[88:89], v[40:41]
	v_mov_b64_e32 v[86:87], v[38:39]
	v_mov_b64_e32 v[84:85], v[36:37]
	v_mov_b64_e32 v[82:83], v[34:35]
	v_mov_b64_e32 v[80:81], v[32:33]
	v_mov_b32_e32 v235, v236
	v_mov_b32_e32 v211, v3
	v_mov_b32_e32 v164, v0
	v_mov_b32_e32 v165, v238
	v_mov_b32_e32 v166, v240
	v_mov_b32_e32 v167, v15
	v_mov_b32_e32 v148, v8
	v_mov_b32_e32 v149, v10
	v_mov_b32_e32 v172, v237
	v_mov_b32_e32 v173, v239
	v_mov_b32_e32 v174, v241
	v_mov_b32_e32 v175, v14
	v_mov_b32_e32 v152, v9
	v_mov_b32_e32 v153, v11
	v_mov_b32_e32 v154, v12

; #define LAS __attribute__((address_space(3)))
; #define MFMA32(a, b, c) __builtin_amdgcn_mfma_f32_32x32x16_bf16((a), (b), (c), 0, 0, 0)
; template <int DQK, int VAR> __device__ __forceinline__ void att_tile_fused(LAS unsigned char* lds, int kt, int mylast, bool& pend, int vs_prev, int vs_cur, int lane_off, int r, int h, ...
;     ...
;     f32x16 S0, S1;
; #pragma unroll
;     for (int i = 0; i < 16; ++i) { S0[i] = 0.f; S1[i] = 0.f; }
;     const LAS unsigned char* kb = lds + (kt & 1) * ATT_KBYTES + r * KP + h * 16;
;     bf16x8 ka[2][2];
;     ka[0][0] = *(const LAS bf16x8*)(kb); ka[0][1] = *(const LAS bf16x8*)(kb + 32 * KP);
; #pragma unroll
;     for (int s = 0; s < NS; ++s) {
;         if (s + 1 < NS) { ka[(s + 1) & 1][0] = *(const LAS bf16x8*)(kb + (s + 1) * 32); ka[(s + 1) & 1][1] = *(const LAS bf16x8*)(kb + 32 * KP + (s + 1) * 32); }
;         S0 = MFMA32(ka[s & 1][0], qf[s], S0); S1 = MFMA32(ka[s & 1][1], qf[s], S1);
;         __builtin_amdgcn_sched_barrier(0);
;     }
;     const LAS unsigned char* vb = lds + ATT_VOFF + (pend ? vs_prev : vs_cur) * ATT_VBYTES + lane_off;
;     bf16x8 va[2][4];
; #pragma unroll
;     for (int js = 0; js < 4; ++js) va[0][js] = *(const LAS bf16x8*)(vb + js * 32);
;     float mx = S0[0];
; #pragma unroll
;     for (int i = 1; i < 16; ++i) mx = fmaxf(mx, S0[i]);
; #pragma unroll
;     for (int i = 0; i < 16; ++i) mx = fmaxf(mx, S1[i]);
;     mx = fmaxf(mx, __shfl_xor(mx, 32));
;     const float mn = fmaxf(mrun, mx), alpha = __builtin_amdgcn_exp2f(mrun - mn);
;     const bool grew = __builtin_amdgcn_ballot_w64(mn > mrun) != 0ull;
;     mrun = mn;
;     float ps = 0.f;
;     u32x4 w0, w1, w2, w3;
;     __builtin_amdgcn_sched_barrier(0);
; #pragma unroll
;     for (int db = 0; db < 4; ++db) {
;         if (db < 3) {
; #pragma unroll
;             for (int js = 0; js < 4; ++js) va[(db + 1) & 1][js] = *(const LAS bf16x8*)(vb + (db + 1) * 32 * VPB + js * 32);
;         }
; #pragma unroll
;         for (int js = 0; js < 4; ++js) {
;             const int c = db * 4 + js;
;             O[db] = MFMA32(va[db & 1][js], pf[js], O[db]);
;             S0[c] = __builtin_amdgcn_exp2f(S0[c] - mn); S1[c] = __builtin_amdgcn_exp2f(S1[c] - mn); ps += S0[c] + S1[c];
.LBB0_818:
	v_add_u32_e32 v0, v230, v212
	ds_read_b128 v[2:5], v0 offset:25600
	ds_read_b128 v[34:37], v0 offset:25632
	s_nop 6
	ds_read_b128 v[18:21], v0 offset:30208
	ds_read_b128 v[38:41], v0 offset:30240
	s_waitcnt lgkmcnt(3)
	v_mfma_f32_32x32x16_bf16 v[2:17], v[2:5], v[144:147], 0
	s_waitcnt lgkmcnt(1)
	v_mfma_f32_32x32x16_bf16 v[18:33], v[18:21], v[144:147], 0
	v_mfma_f32_32x32x16_bf16 v[2:17], v[34:37], v[156:159], v[2:17]
	ds_read_b128 v[34:37], v0 offset:25664
	ds_read_b128 v[42:45], v0 offset:30272
	s_waitcnt lgkmcnt(2)
	v_mfma_f32_32x32x16_bf16 v[18:33], v[38:41], v[156:159], v[18:33]
	s_waitcnt lgkmcnt(1)
	v_mfma_f32_32x32x16_bf16 v[2:17], v[34:37], v[160:163], v[2:17]
	ds_read_b128 v[34:37], v0 offset:25696
	ds_read_b128 v[38:41], v0 offset:30304
	s_waitcnt lgkmcnt(2)
	v_mfma_f32_32x32x16_bf16 v[18:33], v[42:45], v[160:163], v[18:33]
	s_waitcnt lgkmcnt(1)
	v_mfma_f32_32x32x16_bf16 v[2:17], v[34:37], v[168:171], v[2:17]
	s_mulk_i32 s74, 0x4800
	v_add_u32_e32 v66, s74, v233
	s_waitcnt lgkmcnt(0)
	v_mfma_f32_32x32x16_bf16 v[18:33], v[38:41], v[168:171], v[18:33]
	s_nop 7
	v_max_f32_e32 v0, v3, v3
	v_max_f32_e32 v34, v2, v2
	v_max_f32_e32 v0, v34, v0
	v_max3_f32 v0, v0, v4, v5
	v_max3_f32 v0, v0, v6, v7
	v_max3_f32 v0, v0, v8, v9
	v_max3_f32 v0, v0, v10, v11
	v_max3_f32 v0, v0, v12, v13
	v_max3_f32 v0, v0, v14, v15
	v_max3_f32 v0, v0, v16, v17
	v_max3_f32 v0, v0, v18, v19
	v_max3_f32 v0, v0, v20, v21
	v_max3_f32 v0, v0, v22, v23
	v_max3_f32 v0, v0, v24, v25
	v_max3_f32 v0, v0, v26, v27
	v_max3_f32 v0, v0, v28, v29
	v_max3_f32 v0, v0, v30, v31
	v_max3_f32 v0, v0, v32, v33
	v_mov_b32_e32 v50, v0
	s_nop 1
	v_permlane32_swap_b32_e32 v50, v0
	ds_read_b128 v[34:37], v66 offset:51200
	ds_read_b128 v[38:41], v66 offset:51232
	ds_read_b128 v[42:45], v66 offset:51264
	ds_read_b128 v[46:49], v66 offset:51296
	s_waitcnt lgkmcnt(4)
	v_max3_f32 v236, v235, v0, v50
	v_sub_f32_e32 v67, v236, v235
	v_cmp_lt_f32_e32 vcc, 4.0, v67
	v_cndmask_b32_e32 v236, v235, v236, vcc
	v_cmp_gt_f32_e32 vcc, v236, v235
	s_cmp_lg_u64 vcc, 0
	v_sub_f32_e32 v67, v235, v236
	s_cselect_b64 s[36:37], -1, 0
	ds_read_b128 v[50:53], v66 offset:55808
	ds_read_b128 v[54:57], v66 offset:55840
	ds_read_b128 v[58:61], v66 offset:55872
	ds_read_b128 v[62:65], v66 offset:55904
	v_sub_f32_e32 v0, v2, v236
	v_exp_f32_e32 v68, v0
	v_sub_f32_e32 v0, v18, v236
	v_exp_f32_e32 v18, v0
	s_waitcnt lgkmcnt(7)
	v_mfma_f32_32x32x16_bf16 v[80:95], v[34:37], v[164:167], v[80:95]
	v_add_f32_e32 v35, v18, v68
	v_sub_f32_e32 v0, v3, v236
	v_sub_f32_e32 v2, v19, v236
	v_exp_f32_e32 v0, v0
	v_exp_f32_e32 v34, v2
	s_waitcnt lgkmcnt(6)
	v_mfma_f32_32x32x16_bf16 v[80:95], v[38:41], v[148:151], v[80:95]
	v_add_f32_e64 v2, v34, v0
	v_add_f32_e64 v3, v35, v1
	v_add_f32_e32 v3, v2, v3
	v_cvt_pk_bf16_f32 v237, v18, v34
	v_cvt_pk_bf16_f32 v0, v68, v0
	v_sub_f32_e32 v2, v4, v236
	v_exp_f32_e32 v34, v2
	v_sub_f32_e32 v2, v20, v236
	v_exp_f32_e32 v20, v2
	s_waitcnt lgkmcnt(5)
	v_mfma_f32_32x32x16_bf16 v[80:95], v[42:45], v[172:175], v[80:95]
	v_add_f32_e32 v19, v20, v34
	v_sub_f32_e32 v2, v5, v236
	v_sub_f32_e32 v4, v21, v236
	v_exp_f32_e32 v2, v2
	v_exp_f32_e32 v18, v4
	s_waitcnt lgkmcnt(4)
	v_mfma_f32_32x32x16_bf16 v[80:95], v[46:49], v[152:155], v[80:95]
	v_cvt_pk_bf16_f32 v238, v34, v2
	v_add_f32_e64 v4, v18, v2
	v_add_f32_e64 v5, v19, v3
	v_cvt_pk_bf16_f32 v239, v20, v18
	v_add_f32_e64 v42, v4, v4
	v_add_f32_e64 v43, v4, v5
	ds_read_b128 v[2:5], v66 offset:60416
	ds_read_b128 v[18:21], v66 offset:60448
	ds_read_b128 v[34:37], v66 offset:60480
	ds_read_b128 v[38:41], v66 offset:60512
	v_sub_f32_e32 v6, v6, v236
	v_exp_f32_e32 v46, v6
	v_sub_f32_e32 v6, v22, v236
	v_exp_f32_e32 v22, v6
	s_waitcnt lgkmcnt(7)
	v_mfma_f32_32x32x16_bf16 v[96:111], v[50:53], v[164:167], v[96:111]
	v_add_f32_e32 v45, v22, v46
	v_sub_f32_e32 v6, v7, v236
	v_exp_f32_e32 v42, v6
	v_sub_f32_e32 v6, v23, v236
	v_exp_f32_e32 v44, v6
	s_waitcnt lgkmcnt(6)
	v_mfma_f32_32x32x16_bf16 v[96:111], v[54:57], v[148:151], v[96:111]
	v_cvt_pk_bf16_f32 v240, v46, v42
	v_add_f32_e64 v6, v44, v42
	v_add_f32_e64 v7, v45, v43
	v_add_f32_e32 v7, v6, v7
	v_cvt_pk_bf16_f32 v241, v22, v44
	v_sub_f32_e32 v6, v8, v236
	v_exp_f32_e32 v42, v6
	v_sub_f32_e32 v6, v24, v236
	v_exp_f32_e32 v24, v6
	s_waitcnt lgkmcnt(5)
	v_mfma_f32_32x32x16_bf16 v[96:111], v[58:61], v[172:175], v[96:111]
	v_add_f32_e32 v23, v24, v42
	v_sub_f32_e32 v6, v9, v236
	v_sub_f32_e32 v8, v25, v236
	v_exp_f32_e32 v6, v6
	v_exp_f32_e32 v22, v8
	s_waitcnt lgkmcnt(4)
; #define LAS __attribute__((address_space(3)))
; template <int DQK, int VAR> __device__ __forceinline__ void att_tile_fused(LAS unsigned char* lds, int kt, int mylast, bool& pend, int vs_prev, int vs_cur, int lane_off, int r, int h, ...
;     ...
; #pragma unroll
;     for (int db = 0; db < 4; ++db) {
;         if (db < 3) {
; #pragma unroll
;             for (int js = 0; js < 4; ++js) va[(db + 1) & 1][js] = *(const LAS bf16x8*)(vb + (db + 1) * 32 * VPB + js * 32);
;         }
; #pragma unroll
;         for (int js = 0; js < 4; ++js) {
;             const int c = db * 4 + js;
;             O[db] = MFMA32(va[db & 1][js], pf[js], O[db]);
;             S0[c] = __builtin_amdgcn_exp2f(S0[c] - mn); S1[c] = __builtin_amdgcn_exp2f(S1[c] - mn); ps += S0[c] + S1[c];
;             if (c & 1) {
;                 const unsigned a = pk2(S0[c - 1], S0[c]), b = pk2(S1[c - 1], S1[c]);
;                 const int q = c >> 1;
;                 if (q == 0) { w0.x = a; w2.x = b; } else if (q == 1) { w0.y = a; w2.y = b; } else if (q == 2) { w0.z = a; w2.z = b; } else if (q == 3) { w0.w = a; w2.w = b; }
;                 else if (q == 4) { w1.x = a; w3.x = b; } else if (q == 5) { w1.y = a; w3.y = b; } else if (q == 6) { w1.z = a; w3.z = b; } else { w1.w = a; w3.w = b; }
;             }
;             __builtin_amdgcn_sched_barrier(0);
;         }
;     }
;     lrun = lrun * alpha + ps;
;     alpha_p = alpha; grew_p = grew;
;     pf[0] = __builtin_bit_cast(bf16x8, w0); pf[1] = __builtin_bit_cast(bf16x8, w1); pf[2] = __builtin_bit_cast(bf16x8, w2); pf[3] = __builtin_bit_cast(bf16x8, w3);
; template <int DQK, int VAR> __device__ __forceinline__ void attn_core(LAS unsigned char* lds, const bf16_t* Qrow, const bf16_t* Kb, int kpitch, const bf16_t* Vb, int len, ...
;     ...
;         for (int kt = 0; kt < ntiles; kt += 2) {
;             if (VAR != 3 && kt + 2 < ntiles) att_load<DQK>(Kb, kpitch, Vb, len, kt + 2, tid, kA, vA);
;             ATT_TILE(kt);
;             if (VAR != 3 && kt + 1 < ntiles) att_store<DQK>(lds + ((kt + 1) & 1) * ATT_KBYTES, lds + ATT_VOFF + vs_next * ATT_VBYTES, tid, kB, vB);
;             __syncthreads();
;             vs_prev = vs_cur; vs_cur = vs_next; vs_next = (vs_next == 2) ? 0 : vs_next + 1;
;             if (kt + 1 < ntiles) {
;                 if (VAR != 3 && kt + 3 < ntiles) att_load<DQK>(Kb, kpitch, Vb, len, kt + 3, tid, kB, vB);
;                 ATT_TILE(kt + 1);
	v_mfma_f32_32x32x16_bf16 v[96:111], v[62:65], v[152:155], v[96:111]
	v_cvt_pk_bf16_f32 v242, v42, v6
	v_add_f32_e64 v8, v22, v6
	v_add_f32_e64 v9, v23, v7
	v_cvt_pk_bf16_f32 v243, v24, v22
	v_add_f32_e64 v50, v8, v8
	v_add_f32_e64 v51, v8, v9
	ds_read_b128 v[6:9], v66 offset:65024
	ds_read_b128 v[22:25], v66 offset:65056
	ds_read_b128 v[42:45], v66 offset:65088
	ds_read_b128 v[46:49], v66 offset:65120
	v_sub_f32_e32 v10, v10, v236
	v_sub_f32_e32 v26, v26, v236
	v_exp_f32_e32 v10, v10
	v_exp_f32_e32 v26, v26
	s_waitcnt lgkmcnt(7)
	v_mfma_f32_32x32x16_bf16 v[112:127], v[2:5], v[164:167], v[112:127]
	v_add_f32_e32 v3, v26, v10
	v_sub_f32_e32 v2, v11, v236
	v_exp_f32_e32 v50, v2
	v_sub_f32_e32 v2, v27, v236
	v_exp_f32_e32 v2, v2
	s_waitcnt lgkmcnt(6)
	v_mfma_f32_32x32x16_bf16 v[112:127], v[18:21], v[148:151], v[112:127]
	v_cvt_pk_bf16_f32 v244, v10, v50
	v_add_f32_e64 v4, v2, v50
	v_add_f32_e64 v5, v3, v51
	v_add_f32_e32 v5, v4, v5
	v_cvt_pk_bf16_f32 v245, v26, v2
	v_sub_f32_e32 v2, v12, v236
	v_exp_f32_e32 v12, v2
	v_sub_f32_e32 v2, v28, v236
	v_exp_f32_e32 v18, v2
	s_waitcnt lgkmcnt(5)
	v_mfma_f32_32x32x16_bf16 v[112:127], v[34:37], v[172:175], v[112:127]
	v_add_f32_e32 v3, v18, v12
	v_sub_f32_e32 v2, v13, v236
	v_exp_f32_e32 v4, v2
	v_sub_f32_e32 v2, v29, v236
	v_exp_f32_e32 v2, v2
	s_waitcnt lgkmcnt(4)
	v_mfma_f32_32x32x16_bf16 v[112:127], v[38:41], v[152:155], v[112:127]
	v_cvt_pk_bf16_f32 v12, v12, v4
	v_add_f32_e64 v10, v2, v4
	v_add_f32_e64 v11, v3, v5
	v_add_f32_e32 v11, v10, v11
	v_cvt_pk_bf16_f32 v13, v18, v2
	v_sub_f32_e32 v2, v14, v236
	v_exp_f32_e32 v14, v2
	v_sub_f32_e32 v2, v30, v236
	v_exp_f32_e32 v18, v2
	s_waitcnt lgkmcnt(3)
	v_mfma_f32_32x32x16_bf16 v[128:143], v[6:9], v[164:167], v[128:143]
	v_add_f32_e32 v3, v18, v14
	v_sub_f32_e32 v2, v15, v236
	v_exp_f32_e32 v10, v2
	v_sub_f32_e32 v2, v31, v236
	v_exp_f32_e32 v2, v2
	s_waitcnt lgkmcnt(2)
	v_mfma_f32_32x32x16_bf16 v[128:143], v[22:25], v[148:151], v[128:143]
	v_cvt_pk_bf16_f32 v150, v14, v10
	v_add_f32_e64 v4, v2, v10
	v_add_f32_e64 v5, v3, v11
	v_add_f32_e32 v5, v4, v5
	v_cvt_pk_bf16_f32 v8, v18, v2
	v_sub_f32_e32 v2, v16, v236
	v_exp_f32_e32 v9, v2
	v_sub_f32_e32 v2, v32, v236
	v_exp_f32_e32 v10, v2
	s_waitcnt lgkmcnt(1)
	v_mfma_f32_32x32x16_bf16 v[128:143], v[42:45], v[172:175], v[128:143]
	v_add_f32_e32 v3, v10, v9
	v_sub_f32_e32 v2, v17, v236
	v_exp_f32_e32 v4, v2
	v_sub_f32_e32 v2, v33, v236
	v_exp_f32_e32 v2, v2
	s_waitcnt lgkmcnt(0)
	v_mfma_f32_32x32x16_bf16 v[128:143], v[46:49], v[152:155], v[128:143]
	v_cvt_pk_bf16_f32 v151, v9, v4
	v_add_f32_e64 v6, v2, v4
	v_add_f32_e64 v7, v3, v5
	v_cvt_pk_bf16_f32 v155, v10, v2
	v_add_f32_e32 v3, v6, v7
	v_exp_f32_e32 v224, v67
	s_nop 5
	v_mov_b64_e32 v[16:17], v[128:129]
	v_mov_b64_e32 v[48:49], v[112:113]
	v_mov_b64_e32 v[64:65], v[96:97]
	v_fmac_f32_e32 v3, v211, v224
	v_mov_b64_e32 v[32:33], v[80:81]
	v_mov_b64_e32 v[18:19], v[130:131]
	v_mov_b64_e32 v[20:21], v[132:133]
	v_mov_b64_e32 v[22:23], v[134:135]
	v_mov_b64_e32 v[24:25], v[136:137]
	v_mov_b64_e32 v[26:27], v[138:139]
	v_mov_b64_e32 v[28:29], v[140:141]
	v_mov_b64_e32 v[30:31], v[142:143]
	v_mov_b64_e32 v[50:51], v[114:115]
	v_mov_b64_e32 v[52:53], v[116:117]
	v_mov_b64_e32 v[54:55], v[118:119]
	v_mov_b64_e32 v[56:57], v[120:121]
	v_mov_b64_e32 v[58:59], v[122:123]
	v_mov_b64_e32 v[60:61], v[124:125]
	v_mov_b64_e32 v[62:63], v[126:127]
	v_mov_b64_e32 v[66:67], v[98:99]
	v_mov_b64_e32 v[68:69], v[100:101]
	v_mov_b64_e32 v[70:71], v[102:103]
	v_mov_b64_e32 v[72:73], v[104:105]
	v_mov_b64_e32 v[74:75], v[106:107]
	v_mov_b64_e32 v[76:77], v[108:109]
	v_mov_b64_e32 v[78:79], v[110:111]
	v_mov_b64_e32 v[34:35], v[82:83]
	v_mov_b64_e32 v[36:37], v[84:85]
	v_mov_b64_e32 v[38:39], v[86:87]
	v_mov_b64_e32 v[40:41], v[88:89]
	v_mov_b64_e32 v[42:43], v[90:91]
	v_mov_b64_e32 v[44:45], v[92:93]
	v_mov_b64_e32 v[46:47], v[94:95]
	v_mov_b32_e32 v235, v236
	v_mov_b32_e32 v211, v3
	v_mov_b32_e32 v164, v0
	v_mov_b32_e32 v165, v238
	v_mov_b32_e32 v166, v240
	v_mov_b32_e32 v167, v242
	v_mov_b32_e32 v148, v244
	v_mov_b32_e32 v149, v12
	v_mov_b32_e32 v172, v237
	v_mov_b32_e32 v173, v239
	v_mov_b32_e32 v174, v241
	v_mov_b32_e32 v175, v243
	v_mov_b32_e32 v152, v245
	v_mov_b32_e32 v153, v13
	v_mov_b32_e32 v154, v8
	s_andn2_b64 vcc, exec, s[30:31]
	s_cbranch_vccz .LBB0_811
	s_branch .LBB0_812

; #define LAS __attribute__((address_space(3)))
; #define MFMA32(a, b, c) __builtin_amdgcn_mfma_f32_32x32x16_bf16((a), (b), (c), 0, 0, 0)
; template <int DQK, int VAR> __device__ __forceinline__ void att_tile_fused(LAS unsigned char* lds, int kt, int mylast, bool& pend, int vs_prev, int vs_cur, int lane_off, int r, int h, ...
;     ...
;     f32x16 S0, S1;
; #pragma unroll
;     for (int i = 0; i < 16; ++i) { S0[i] = 0.f; S1[i] = 0.f; }
;     const LAS unsigned char* kb = lds + (kt & 1) * ATT_KBYTES + r * KP + h * 16;
;     bf16x8 ka[2][2];
;     ka[0][0] = *(const LAS bf16x8*)(kb); ka[0][1] = *(const LAS bf16x8*)(kb + 32 * KP);
; #pragma unroll
;     for (int s = 0; s < NS; ++s) {
;         if (s + 1 < NS) { ka[(s + 1) & 1][0] = *(const LAS bf16x8*)(kb + (s + 1) * 32); ka[(s + 1) & 1][1] = *(const LAS bf16x8*)(kb + 32 * KP + (s + 1) * 32); }
;         S0 = MFMA32(ka[s & 1][0], qf[s], S0); S1 = MFMA32(ka[s & 1][1], qf[s], S1);
;         __builtin_amdgcn_sched_barrier(0);
;     }
;     const LAS unsigned char* vb = lds + ATT_VOFF + (pend ? vs_prev : vs_cur) * ATT_VBYTES + lane_off;
;     bf16x8 va[2][4];
; #pragma unroll
;     for (int js = 0; js < 4; ++js) va[0][js] = *(const LAS bf16x8*)(vb + js * 32);
;     float mx = S0[0];
; #pragma unroll
;     for (int i = 1; i < 16; ++i) mx = fmaxf(mx, S0[i]);
; #pragma unroll
;     for (int i = 0; i < 16; ++i) mx = fmaxf(mx, S1[i]);
;     mx = fmaxf(mx, __shfl_xor(mx, 32));
;     const float mn = fmaxf(mrun, mx), alpha = __builtin_amdgcn_exp2f(mrun - mn);
;     const bool grew = __builtin_amdgcn_ballot_w64(mn > mrun) != 0ull;
;     mrun = mn;
;     float ps = 0.f;
;     u32x4 w0, w1, w2, w3;
;     __builtin_amdgcn_sched_barrier(0);
; #pragma unroll
;     for (int db = 0; db < 4; ++db) {
;         if (db < 3) {
; #pragma unroll
;             for (int js = 0; js < 4; ++js) va[(db + 1) & 1][js] = *(const LAS bf16x8*)(vb + (db + 1) * 32 * VPB + js * 32);
;         }
; #pragma unroll
;         for (int js = 0; js < 4; ++js) {
;             const int c = db * 4 + js;
;             O[db] = MFMA32(va[db & 1][js], pf[js], O[db]);
;             S0[c] = __builtin_amdgcn_exp2f(S0[c] - mn); S1[c] = __builtin_amdgcn_exp2f(S1[c] - mn); ps += S0[c] + S1[c];
.LBB0_841:
	s_andn2_b64 vcc, exec, s[30:31]
	s_mov_b64 s[30:31], 0
	s_cbranch_vccnz .LBB0_843
	v_add_u32_e32 v0, v211, v186
	ds_read_b128 v[66:69], v0
	ds_read_b128 v[98:101], v0 offset:32
	ds_read_b128 v[82:85], v0 offset:4608
	ds_read_b128 v[102:105], v0 offset:4640
	s_waitcnt lgkmcnt(3)
	v_mfma_f32_32x32x16_bf16 v[66:81], v[66:69], v[138:141], 0
	s_waitcnt lgkmcnt(1)
	v_mfma_f32_32x32x16_bf16 v[82:97], v[82:85], v[138:141], 0
	v_mfma_f32_32x32x16_bf16 v[66:81], v[98:101], v[142:145], v[66:81]
	ds_read_b128 v[98:101], v0 offset:64
	ds_read_b128 v[106:109], v0 offset:4672
	s_waitcnt lgkmcnt(2)
	v_mfma_f32_32x32x16_bf16 v[82:97], v[102:105], v[142:145], v[82:97]
	s_waitcnt lgkmcnt(1)
	v_mfma_f32_32x32x16_bf16 v[66:81], v[98:101], v[150:153], v[66:81]
	ds_read_b128 v[98:101], v0 offset:96
	ds_read_b128 v[102:105], v0 offset:4704
	s_waitcnt lgkmcnt(2)
	v_mfma_f32_32x32x16_bf16 v[82:97], v[106:109], v[150:153], v[82:97]
	s_waitcnt lgkmcnt(1)
	v_mfma_f32_32x32x16_bf16 v[66:81], v[98:101], v[158:161], v[66:81]
	s_and_b64 s[28:29], s[28:29], exec
	s_cselect_b32 s14, s25, s37
	s_mulk_i32 s14, 0x4800
	v_add_u32_e32 v198, s14, v214
	s_waitcnt lgkmcnt(0)
	v_mfma_f32_32x32x16_bf16 v[82:97], v[102:105], v[158:161], v[82:97]
	s_nop 5
	v_max_f32_e32 v0, v67, v67
	v_max_f32_e32 v98, v66, v66
	v_max_f32_e32 v0, v98, v0
	v_max3_f32 v0, v0, v68, v69
	v_max3_f32 v0, v0, v70, v71
	v_max3_f32 v0, v0, v72, v73
	v_max3_f32 v0, v0, v74, v75
	v_max3_f32 v0, v0, v76, v77
	v_max3_f32 v0, v0, v78, v79
	v_max3_f32 v0, v0, v80, v81
	v_max3_f32 v0, v0, v82, v83
	v_max3_f32 v0, v0, v84, v85
	v_max3_f32 v0, v0, v86, v87
	v_max3_f32 v0, v0, v88, v89
	v_max3_f32 v0, v0, v90, v91
	v_max3_f32 v0, v0, v92, v93
	v_max3_f32 v0, v0, v94, v95
	v_max3_f32 v0, v0, v96, v97
	v_mov_b32_e32 v114, v0
	s_nop 1
	v_permlane32_swap_b32_e32 v114, v0
	ds_read_b128 v[98:101], v198 offset:51200
	ds_read_b128 v[102:105], v198 offset:51232
	ds_read_b128 v[106:109], v198 offset:51264
	ds_read_b128 v[110:113], v198 offset:51296
	s_waitcnt lgkmcnt(4)
	v_max3_f32 v217, v216, v0, v114
	v_sub_f32_e32 v218, v217, v216
	v_cmp_lt_f32_e32 vcc, 4.0, v218
	v_cndmask_b32_e32 v217, v216, v217, vcc
	v_cmp_gt_f32_e32 vcc, v217, v216
	s_cmp_lg_u64 vcc, 0
	s_cselect_b64 s[30:31], -1, 0
	v_sub_f32_e32 v218, v216, v217
	ds_read_b128 v[114:117], v198 offset:55808
	ds_read_b128 v[118:121], v198 offset:55840
	ds_read_b128 v[122:125], v198 offset:55872
	ds_read_b128 v[126:129], v198 offset:55904
	v_sub_f32_e32 v0, v66, v217
	v_exp_f32_e32 v216, v0
	v_sub_f32_e32 v0, v82, v217
	v_exp_f32_e32 v82, v0
	s_waitcnt lgkmcnt(7)
	v_mfma_f32_32x32x16_bf16 v[2:17], v[98:101], v[146:149], v[2:17]
	v_add_f32_e32 v99, v82, v216
	v_sub_f32_e32 v0, v67, v217
	v_sub_f32_e32 v66, v83, v217
	v_exp_f32_e32 v0, v0
	v_exp_f32_e32 v98, v66
	s_waitcnt lgkmcnt(6)
	v_mfma_f32_32x32x16_bf16 v[2:17], v[102:105], v[130:133], v[2:17]
	v_add_f32_e64 v66, v98, v0
	v_add_f32_e64 v67, v99, v1
	v_add_f32_e32 v67, v66, v67
	v_cvt_pk_bf16_f32 v219, v82, v98
	v_cvt_pk_bf16_f32 v0, v216, v0
	v_sub_f32_e32 v66, v68, v217
	v_exp_f32_e32 v98, v66
	v_sub_f32_e32 v66, v84, v217
	v_exp_f32_e32 v84, v66
	s_waitcnt lgkmcnt(5)
	v_mfma_f32_32x32x16_bf16 v[2:17], v[106:109], v[154:157], v[2:17]
	v_add_f32_e32 v83, v84, v98
	v_sub_f32_e32 v66, v69, v217
	v_sub_f32_e32 v68, v85, v217
	v_exp_f32_e32 v66, v66
	v_exp_f32_e32 v82, v68
	s_waitcnt lgkmcnt(4)
	v_mfma_f32_32x32x16_bf16 v[2:17], v[110:113], v[134:137], v[2:17]
	v_cvt_pk_bf16_f32 v220, v98, v66
	v_add_f32_e64 v68, v82, v66
	v_add_f32_e64 v69, v83, v67
	v_cvt_pk_bf16_f32 v221, v84, v82
	v_add_f32_e64 v106, v68, v68
	v_add_f32_e64 v107, v68, v69
	ds_read_b128 v[66:69], v198 offset:60416
	ds_read_b128 v[82:85], v198 offset:60448
	ds_read_b128 v[98:101], v198 offset:60480
	ds_read_b128 v[102:105], v198 offset:60512
	v_sub_f32_e32 v70, v70, v217
	v_exp_f32_e32 v110, v70
	v_sub_f32_e32 v70, v86, v217
	v_exp_f32_e32 v86, v70
	s_waitcnt lgkmcnt(7)
	v_mfma_f32_32x32x16_bf16 v[18:33], v[114:117], v[146:149], v[18:33]
	v_add_f32_e32 v109, v86, v110
	v_sub_f32_e32 v70, v71, v217
	v_exp_f32_e32 v106, v70
	v_sub_f32_e32 v70, v87, v217
	v_exp_f32_e32 v108, v70
	s_waitcnt lgkmcnt(6)
	v_mfma_f32_32x32x16_bf16 v[18:33], v[118:121], v[130:133], v[18:33]
	v_cvt_pk_bf16_f32 v222, v110, v106
	v_add_f32_e64 v70, v108, v106
	v_add_f32_e64 v71, v109, v107
	v_add_f32_e32 v71, v70, v71
	v_cvt_pk_bf16_f32 v223, v86, v108
	v_sub_f32_e32 v70, v72, v217
	v_exp_f32_e32 v106, v70
	v_sub_f32_e32 v70, v88, v217
	v_exp_f32_e32 v88, v70
	s_waitcnt lgkmcnt(5)
; #define LAS __attribute__((address_space(3)))
; __device__ __forceinline__ unsigned pk2(float lo, float hi) { f32x2_t v = {lo, hi}; bf16x2_t b = __builtin_convertvector(v, bf16x2_t); return __builtin_bit_cast(unsigned, b); }
; #define MFMA32(a, b, c) __builtin_amdgcn_mfma_f32_32x32x16_bf16((a), (b), (c), 0, 0, 0)
; template <int DQK, int VAR> __device__ __forceinline__ void att_tile_fused(LAS unsigned char* lds, int kt, int mylast, bool& pend, int vs_prev, int vs_cur, int lane_off, int r, int h, ...
;     ...
; #pragma unroll
;     for (int db = 0; db < 4; ++db) {
;         if (db < 3) {
; #pragma unroll
;             for (int js = 0; js < 4; ++js) va[(db + 1) & 1][js] = *(const LAS bf16x8*)(vb + (db + 1) * 32 * VPB + js * 32);
;         }
; #pragma unroll
;         for (int js = 0; js < 4; ++js) {
;             const int c = db * 4 + js;
;             O[db] = MFMA32(va[db & 1][js], pf[js], O[db]);
;             S0[c] = __builtin_amdgcn_exp2f(S0[c] - mn); S1[c] = __builtin_amdgcn_exp2f(S1[c] - mn); ps += S0[c] + S1[c];
;             if (c & 1) {
;                 const unsigned a = pk2(S0[c - 1], S0[c]), b = pk2(S1[c - 1], S1[c]);
;                 const int q = c >> 1;
;                 if (q == 0) { w0.x = a; w2.x = b; } else if (q == 1) { w0.y = a; w2.y = b; } else if (q == 2) { w0.z = a; w2.z = b; } else if (q == 3) { w0.w = a; w2.w = b; }
;                 else if (q == 4) { w1.x = a; w3.x = b; } else if (q == 5) { w1.y = a; w3.y = b; } else if (q == 6) { w1.z = a; w3.z = b; } else { w1.w = a; w3.w = b; }
;             }
;             __builtin_amdgcn_sched_barrier(0);
;         }
;     }
;     lrun = lrun * alpha + ps;
;     alpha_p = alpha; grew_p = grew;
;     pf[0] = __builtin_bit_cast(bf16x8, w0); pf[1] = __builtin_bit_cast(bf16x8, w1); pf[2] = __builtin_bit_cast(bf16x8, w2); pf[3] = __builtin_bit_cast(bf16x8, w3);
	v_mfma_f32_32x32x16_bf16 v[18:33], v[122:125], v[154:157], v[18:33]
	v_add_f32_e32 v87, v88, v106
	v_sub_f32_e32 v70, v73, v217
	v_sub_f32_e32 v72, v89, v217
	v_exp_f32_e32 v70, v70
	v_exp_f32_e32 v86, v72
	s_waitcnt lgkmcnt(4)
	v_mfma_f32_32x32x16_bf16 v[18:33], v[126:129], v[134:137], v[18:33]
	v_cvt_pk_bf16_f32 v224, v106, v70
	v_add_f32_e64 v72, v86, v70
	v_add_f32_e64 v73, v87, v71
	v_cvt_pk_bf16_f32 v230, v88, v86
	v_add_f32_e64 v114, v72, v72
	v_add_f32_e64 v115, v72, v73
	ds_read_b128 v[70:73], v198 offset:65024
	ds_read_b128 v[86:89], v198 offset:65056
	ds_read_b128 v[106:109], v198 offset:65088
	ds_read_b128 v[110:113], v198 offset:65120
	v_sub_f32_e32 v74, v74, v217
	v_sub_f32_e32 v90, v90, v217
	v_exp_f32_e32 v74, v74
	v_exp_f32_e32 v90, v90
	s_waitcnt lgkmcnt(7)
	v_mfma_f32_32x32x16_bf16 v[34:49], v[66:69], v[146:149], v[34:49]
	v_add_f32_e32 v67, v90, v74
	v_sub_f32_e32 v66, v75, v217
	v_exp_f32_e32 v114, v66
	v_sub_f32_e32 v66, v91, v217
	v_exp_f32_e32 v66, v66
	s_waitcnt lgkmcnt(6)
	v_mfma_f32_32x32x16_bf16 v[34:49], v[82:85], v[130:133], v[34:49]
	v_cvt_pk_bf16_f32 v231, v74, v114
	v_add_f32_e64 v68, v66, v114
	v_add_f32_e64 v69, v67, v115
	v_add_f32_e32 v69, v68, v69
	v_cvt_pk_bf16_f32 v232, v90, v66
	v_sub_f32_e32 v66, v76, v217
	v_exp_f32_e32 v76, v66
	v_sub_f32_e32 v66, v92, v217
	v_exp_f32_e32 v82, v66
	s_waitcnt lgkmcnt(5)
	v_mfma_f32_32x32x16_bf16 v[34:49], v[98:101], v[154:157], v[34:49]
	v_add_f32_e32 v67, v82, v76
	v_sub_f32_e32 v66, v77, v217
	v_exp_f32_e32 v68, v66
	v_sub_f32_e32 v66, v93, v217
	v_exp_f32_e32 v66, v66
	s_waitcnt lgkmcnt(4)
	v_mfma_f32_32x32x16_bf16 v[34:49], v[102:105], v[134:137], v[34:49]
	v_cvt_pk_bf16_f32 v233, v76, v68
	v_add_f32_e64 v74, v66, v68
	v_add_f32_e64 v75, v67, v69
	v_add_f32_e32 v75, v74, v75
	v_cvt_pk_bf16_f32 v234, v82, v66
	v_sub_f32_e32 v66, v78, v217
	v_exp_f32_e32 v76, v66
	v_sub_f32_e32 v66, v94, v217
	v_exp_f32_e32 v77, v66
	s_waitcnt lgkmcnt(3)
	v_mfma_f32_32x32x16_bf16 v[50:65], v[70:73], v[146:149], v[50:65]
	v_add_f32_e32 v67, v77, v76
	v_sub_f32_e32 v66, v79, v217
	v_exp_f32_e32 v74, v66
	v_sub_f32_e32 v66, v95, v217
	v_exp_f32_e32 v66, v66
	s_waitcnt lgkmcnt(2)
	v_mfma_f32_32x32x16_bf16 v[50:65], v[86:89], v[130:133], v[50:65]
	v_cvt_pk_bf16_f32 v132, v76, v74
	v_add_f32_e64 v68, v66, v74
	v_add_f32_e64 v69, v67, v75
	v_add_f32_e32 v69, v68, v69
	v_cvt_pk_bf16_f32 v235, v77, v66
	v_sub_f32_e32 v66, v80, v217
	v_exp_f32_e32 v72, v66
	v_sub_f32_e32 v66, v96, v217
	v_exp_f32_e32 v73, v66
	s_waitcnt lgkmcnt(1)
	v_mfma_f32_32x32x16_bf16 v[50:65], v[106:109], v[154:157], v[50:65]
	v_add_f32_e32 v67, v73, v72
	v_sub_f32_e32 v66, v81, v217
	v_exp_f32_e32 v68, v66
	v_sub_f32_e32 v66, v97, v217
	v_exp_f32_e32 v66, v66
	s_waitcnt lgkmcnt(0)
	v_mfma_f32_32x32x16_bf16 v[50:65], v[110:113], v[134:137], v[50:65]
	v_cvt_pk_bf16_f32 v133, v72, v68
	v_add_f32_e64 v70, v66, v68
	v_add_f32_e64 v71, v67, v69
	v_add_f32_e32 v130, v70, v71
	v_cvt_pk_bf16_f32 v137, v73, v66
	v_exp_f32_e32 v198, v218
	s_nop 5
	v_mov_b64_e32 v[128:129], v[64:65]
	v_mov_b64_e32 v[112:113], v[48:49]
	v_mov_b64_e32 v[96:97], v[32:33]
	v_fmac_f32_e32 v130, v187, v198
	v_mov_b64_e32 v[80:81], v[16:17]
	v_mov_b64_e32 v[126:127], v[62:63]
	v_mov_b64_e32 v[124:125], v[60:61]
	v_mov_b64_e32 v[122:123], v[58:59]
	v_mov_b64_e32 v[120:121], v[56:57]
	v_mov_b64_e32 v[118:119], v[54:55]
	v_mov_b64_e32 v[116:117], v[52:53]
	v_mov_b64_e32 v[114:115], v[50:51]
	v_mov_b64_e32 v[110:111], v[46:47]
	v_mov_b64_e32 v[108:109], v[44:45]
	v_mov_b64_e32 v[106:107], v[42:43]
	v_mov_b64_e32 v[104:105], v[40:41]
	v_mov_b64_e32 v[102:103], v[38:39]
	v_mov_b64_e32 v[100:101], v[36:37]
	v_mov_b64_e32 v[98:99], v[34:35]
	v_mov_b64_e32 v[94:95], v[30:31]
	v_mov_b64_e32 v[92:93], v[28:29]
	v_mov_b64_e32 v[90:91], v[26:27]
	v_mov_b64_e32 v[88:89], v[24:25]
	v_mov_b64_e32 v[86:87], v[22:23]
	v_mov_b64_e32 v[84:85], v[20:21]
	v_mov_b64_e32 v[82:83], v[18:19]
	v_mov_b64_e32 v[78:79], v[14:15]
	v_mov_b64_e32 v[76:77], v[12:13]
	v_mov_b64_e32 v[74:75], v[10:11]
	v_mov_b64_e32 v[72:73], v[8:9]
	v_mov_b64_e32 v[70:71], v[6:7]
	v_mov_b64_e32 v[68:69], v[4:5]
	v_mov_b64_e32 v[66:67], v[2:3]
	v_mov_b32_e32 v216, v217
	v_mov_b32_e32 v187, v130
	v_mov_b32_e32 v146, v0
	v_mov_b32_e32 v147, v220
	v_mov_b32_e32 v148, v222
	v_mov_b32_e32 v149, v224
	v_mov_b32_e32 v130, v231
	v_mov_b32_e32 v131, v233
	v_mov_b32_e32 v154, v219
	v_mov_b32_e32 v155, v221
	v_mov_b32_e32 v156, v223
	v_mov_b32_e32 v157, v230
	v_mov_b32_e32 v134, v232
	v_mov_b32_e32 v135, v234
	v_mov_b32_e32 v136, v235

; #define LAS __attribute__((address_space(3)))
; #define MFMA32(a, b, c) __builtin_amdgcn_mfma_f32_32x32x16_bf16((a), (b), (c), 0, 0, 0)
; template <int DQK, int VAR> __device__ __forceinline__ void att_tile_fused(LAS unsigned char* lds, int kt, int mylast, bool& pend, int vs_prev, int vs_cur, int lane_off, int r, int h, ...
;     ...
;     f32x16 S0, S1;
; #pragma unroll
;     for (int i = 0; i < 16; ++i) { S0[i] = 0.f; S1[i] = 0.f; }
;     const LAS unsigned char* kb = lds + (kt & 1) * ATT_KBYTES + r * KP + h * 16;
;     bf16x8 ka[2][2];
;     ka[0][0] = *(const LAS bf16x8*)(kb); ka[0][1] = *(const LAS bf16x8*)(kb + 32 * KP);
; #pragma unroll
;     for (int s = 0; s < NS; ++s) {
;         if (s + 1 < NS) { ka[(s + 1) & 1][0] = *(const LAS bf16x8*)(kb + (s + 1) * 32); ka[(s + 1) & 1][1] = *(const LAS bf16x8*)(kb + 32 * KP + (s + 1) * 32); }
;         S0 = MFMA32(ka[s & 1][0], qf[s], S0); S1 = MFMA32(ka[s & 1][1], qf[s], S1);
;         __builtin_amdgcn_sched_barrier(0);
;     }
;     const LAS unsigned char* vb = lds + ATT_VOFF + (pend ? vs_prev : vs_cur) * ATT_VBYTES + lane_off;
;     bf16x8 va[2][4];
; #pragma unroll
;     for (int js = 0; js < 4; ++js) va[0][js] = *(const LAS bf16x8*)(vb + js * 32);
;     float mx = S0[0];
; #pragma unroll
;     for (int i = 1; i < 16; ++i) mx = fmaxf(mx, S0[i]);
; #pragma unroll
;     for (int i = 0; i < 16; ++i) mx = fmaxf(mx, S1[i]);
;     mx = fmaxf(mx, __shfl_xor(mx, 32));
;     const float mn = fmaxf(mrun, mx), alpha = __builtin_amdgcn_exp2f(mrun - mn);
;     const bool grew = __builtin_amdgcn_ballot_w64(mn > mrun) != 0ull;
;     mrun = mn;
;     float ps = 0.f;
;     u32x4 w0, w1, w2, w3;
;     __builtin_amdgcn_sched_barrier(0);
; #pragma unroll
;     for (int db = 0; db < 4; ++db) {
;         if (db < 3) {
; #pragma unroll
;             for (int js = 0; js < 4; ++js) va[(db + 1) & 1][js] = *(const LAS bf16x8*)(vb + (db + 1) * 32 * VPB + js * 32);
;         }
; #pragma unroll
;         for (int js = 0; js < 4; ++js) {
;             const int c = db * 4 + js;
;             O[db] = MFMA32(va[db & 1][js], pf[js], O[db]);
;             S0[c] = __builtin_amdgcn_exp2f(S0[c] - mn); S1[c] = __builtin_amdgcn_exp2f(S1[c] - mn); ps += S0[c] + S1[c];
.LBB0_860:
	v_add_u32_e32 v0, v211, v186
	ds_read_b128 v[2:5], v0 offset:25600
	ds_read_b128 v[34:37], v0 offset:25632
	ds_read_b128 v[18:21], v0 offset:30208
	ds_read_b128 v[38:41], v0 offset:30240
	s_waitcnt lgkmcnt(3)
	v_mfma_f32_32x32x16_bf16 v[2:17], v[2:5], v[138:141], 0
	s_waitcnt lgkmcnt(1)
	v_mfma_f32_32x32x16_bf16 v[18:33], v[18:21], v[138:141], 0
	v_mfma_f32_32x32x16_bf16 v[2:17], v[34:37], v[142:145], v[2:17]
	ds_read_b128 v[34:37], v0 offset:25664
	ds_read_b128 v[42:45], v0 offset:30272
	s_waitcnt lgkmcnt(2)
	v_mfma_f32_32x32x16_bf16 v[18:33], v[38:41], v[142:145], v[18:33]
	s_waitcnt lgkmcnt(1)
	v_mfma_f32_32x32x16_bf16 v[2:17], v[34:37], v[150:153], v[2:17]
	ds_read_b128 v[34:37], v0 offset:25696
	ds_read_b128 v[38:41], v0 offset:30304
	s_waitcnt lgkmcnt(2)
	v_mfma_f32_32x32x16_bf16 v[18:33], v[42:45], v[150:153], v[18:33]
	s_waitcnt lgkmcnt(1)
	v_mfma_f32_32x32x16_bf16 v[2:17], v[34:37], v[158:161], v[2:17]
	s_mulk_i32 s37, 0x4800
	v_add_u32_e32 v198, s37, v214
	s_waitcnt lgkmcnt(0)
	v_mfma_f32_32x32x16_bf16 v[18:33], v[38:41], v[158:161], v[18:33]
	s_nop 7
	v_max_f32_e32 v0, v3, v3
	v_max_f32_e32 v34, v2, v2
	v_max_f32_e32 v0, v34, v0
	v_max3_f32 v0, v0, v4, v5
	v_max3_f32 v0, v0, v6, v7
	v_max3_f32 v0, v0, v8, v9
	v_max3_f32 v0, v0, v10, v11
	v_max3_f32 v0, v0, v12, v13
	v_max3_f32 v0, v0, v14, v15
	v_max3_f32 v0, v0, v16, v17
	v_max3_f32 v0, v0, v18, v19
	v_max3_f32 v0, v0, v20, v21
	v_max3_f32 v0, v0, v22, v23
	v_max3_f32 v0, v0, v24, v25
	v_max3_f32 v0, v0, v26, v27
	v_max3_f32 v0, v0, v28, v29
	v_max3_f32 v0, v0, v30, v31
	v_max3_f32 v0, v0, v32, v33
	v_mov_b32_e32 v50, v0
	s_nop 1
	v_permlane32_swap_b32_e32 v50, v0
	ds_read_b128 v[34:37], v198 offset:51200
	ds_read_b128 v[38:41], v198 offset:51232
	ds_read_b128 v[42:45], v198 offset:51264
	ds_read_b128 v[46:49], v198 offset:51296
	s_waitcnt lgkmcnt(4)
	v_max3_f32 v217, v216, v0, v50
	v_sub_f32_e32 v218, v217, v216
	v_cmp_lt_f32_e32 vcc, 4.0, v218
	v_cndmask_b32_e32 v217, v216, v217, vcc
	v_cmp_gt_f32_e32 vcc, v217, v216
	s_cmp_lg_u64 vcc, 0
	s_cselect_b64 s[30:31], -1, 0
	v_sub_f32_e32 v218, v216, v217
	ds_read_b128 v[50:53], v198 offset:55808
	ds_read_b128 v[54:57], v198 offset:55840
	ds_read_b128 v[58:61], v198 offset:55872
	ds_read_b128 v[62:65], v198 offset:55904
	v_sub_f32_e32 v0, v2, v217
	v_exp_f32_e32 v216, v0
	v_sub_f32_e32 v0, v18, v217
	v_exp_f32_e32 v18, v0
	s_waitcnt lgkmcnt(7)
	v_mfma_f32_32x32x16_bf16 v[66:81], v[34:37], v[146:149], v[66:81]
	v_add_f32_e32 v35, v18, v216
	v_sub_f32_e32 v0, v3, v217
	v_sub_f32_e32 v2, v19, v217
	v_exp_f32_e32 v0, v0
	v_exp_f32_e32 v34, v2
	s_waitcnt lgkmcnt(6)
	v_mfma_f32_32x32x16_bf16 v[66:81], v[38:41], v[130:133], v[66:81]
	v_add_f32_e64 v2, v34, v0
	v_add_f32_e64 v3, v35, v1
	v_add_f32_e32 v3, v2, v3
	v_cvt_pk_bf16_f32 v219, v18, v34
	v_cvt_pk_bf16_f32 v0, v216, v0
	v_sub_f32_e32 v2, v4, v217
	v_exp_f32_e32 v34, v2
	v_sub_f32_e32 v2, v20, v217
	v_exp_f32_e32 v20, v2
	s_waitcnt lgkmcnt(5)
	v_mfma_f32_32x32x16_bf16 v[66:81], v[42:45], v[154:157], v[66:81]
	v_add_f32_e32 v19, v20, v34
	v_sub_f32_e32 v2, v5, v217
	v_sub_f32_e32 v4, v21, v217
	v_exp_f32_e32 v2, v2
	v_exp_f32_e32 v18, v4
	s_waitcnt lgkmcnt(4)
	v_mfma_f32_32x32x16_bf16 v[66:81], v[46:49], v[134:137], v[66:81]
	v_cvt_pk_bf16_f32 v220, v34, v2
	v_add_f32_e64 v4, v18, v2
	v_add_f32_e64 v5, v19, v3
	v_cvt_pk_bf16_f32 v221, v20, v18
	v_add_f32_e64 v42, v4, v4
	v_add_f32_e64 v43, v4, v5
	ds_read_b128 v[2:5], v198 offset:60416
	ds_read_b128 v[18:21], v198 offset:60448
	ds_read_b128 v[34:37], v198 offset:60480
	ds_read_b128 v[38:41], v198 offset:60512
	v_sub_f32_e32 v6, v6, v217
	v_exp_f32_e32 v46, v6
	v_sub_f32_e32 v6, v22, v217
	v_exp_f32_e32 v22, v6
	s_waitcnt lgkmcnt(7)
	v_mfma_f32_32x32x16_bf16 v[82:97], v[50:53], v[146:149], v[82:97]
	v_add_f32_e32 v45, v22, v46
	v_sub_f32_e32 v6, v7, v217
	v_exp_f32_e32 v42, v6
	v_sub_f32_e32 v6, v23, v217
	v_exp_f32_e32 v44, v6
	s_waitcnt lgkmcnt(6)
	v_mfma_f32_32x32x16_bf16 v[82:97], v[54:57], v[130:133], v[82:97]
	v_cvt_pk_bf16_f32 v222, v46, v42
	v_add_f32_e64 v6, v44, v42
	v_add_f32_e64 v7, v45, v43
	v_add_f32_e32 v7, v6, v7
	v_cvt_pk_bf16_f32 v223, v22, v44
	v_sub_f32_e32 v6, v8, v217
	v_exp_f32_e32 v42, v6
	v_sub_f32_e32 v6, v24, v217
	v_exp_f32_e32 v24, v6
	s_waitcnt lgkmcnt(5)
	v_mfma_f32_32x32x16_bf16 v[82:97], v[58:61], v[154:157], v[82:97]
	v_add_f32_e32 v23, v24, v42
	v_sub_f32_e32 v6, v9, v217
	v_sub_f32_e32 v8, v25, v217
	v_exp_f32_e32 v6, v6
	v_exp_f32_e32 v22, v8
	s_waitcnt lgkmcnt(4)
; #define LAS __attribute__((address_space(3)))
; template <int DQK, int VAR> __device__ __forceinline__ void att_tile_fused(LAS unsigned char* lds, int kt, int mylast, bool& pend, int vs_prev, int vs_cur, int lane_off, int r, int h, ...
;     ...
; #pragma unroll
;     for (int db = 0; db < 4; ++db) {
;         if (db < 3) {
; #pragma unroll
;             for (int js = 0; js < 4; ++js) va[(db + 1) & 1][js] = *(const LAS bf16x8*)(vb + (db + 1) * 32 * VPB + js * 32);
;         }
; #pragma unroll
;         for (int js = 0; js < 4; ++js) {
;             const int c = db * 4 + js;
;             O[db] = MFMA32(va[db & 1][js], pf[js], O[db]);
;             S0[c] = __builtin_amdgcn_exp2f(S0[c] - mn); S1[c] = __builtin_amdgcn_exp2f(S1[c] - mn); ps += S0[c] + S1[c];
;             if (c & 1) {
;                 const unsigned a = pk2(S0[c - 1], S0[c]), b = pk2(S1[c - 1], S1[c]);
;                 const int q = c >> 1;
;                 if (q == 0) { w0.x = a; w2.x = b; } else if (q == 1) { w0.y = a; w2.y = b; } else if (q == 2) { w0.z = a; w2.z = b; } else if (q == 3) { w0.w = a; w2.w = b; }
;                 else if (q == 4) { w1.x = a; w3.x = b; } else if (q == 5) { w1.y = a; w3.y = b; } else if (q == 6) { w1.z = a; w3.z = b; } else { w1.w = a; w3.w = b; }
;             }
;             __builtin_amdgcn_sched_barrier(0);
;         }
;     }
;     lrun = lrun * alpha + ps;
;     alpha_p = alpha; grew_p = grew;
;     pf[0] = __builtin_bit_cast(bf16x8, w0); pf[1] = __builtin_bit_cast(bf16x8, w1); pf[2] = __builtin_bit_cast(bf16x8, w2); pf[3] = __builtin_bit_cast(bf16x8, w3);
; template <int DQK, int VAR> __device__ __forceinline__ void attn_core(LAS unsigned char* lds, const bf16_t* Qrow, const bf16_t* Kb, int kpitch, const bf16_t* Vb, int len, ...
;     ...
;         for (int kt = 0; kt < ntiles; kt += 2) {
;             if (VAR != 3 && kt + 2 < ntiles) att_load<DQK>(Kb, kpitch, Vb, len, kt + 2, tid, kA, vA);
;             ATT_TILE(kt);
;             if (VAR != 3 && kt + 1 < ntiles) att_store<DQK>(lds + ((kt + 1) & 1) * ATT_KBYTES, lds + ATT_VOFF + vs_next * ATT_VBYTES, tid, kB, vB);
;             __syncthreads();
;             vs_prev = vs_cur; vs_cur = vs_next; vs_next = (vs_next == 2) ? 0 : vs_next + 1;
;             if (kt + 1 < ntiles) {
;                 if (VAR != 3 && kt + 3 < ntiles) att_load<DQK>(Kb, kpitch, Vb, len, kt + 3, tid, kB, vB);
;                 ATT_TILE(kt + 1);
	v_mfma_f32_32x32x16_bf16 v[82:97], v[62:65], v[134:137], v[82:97]
	v_cvt_pk_bf16_f32 v224, v42, v6
	v_add_f32_e64 v8, v22, v6
	v_add_f32_e64 v9, v23, v7
	v_cvt_pk_bf16_f32 v230, v24, v22
	v_add_f32_e64 v50, v8, v8
	v_add_f32_e64 v51, v8, v9
	ds_read_b128 v[6:9], v198 offset:65024
	ds_read_b128 v[22:25], v198 offset:65056
	ds_read_b128 v[42:45], v198 offset:65088
	ds_read_b128 v[46:49], v198 offset:65120
	v_sub_f32_e32 v10, v10, v217
	v_sub_f32_e32 v26, v26, v217
	v_exp_f32_e32 v10, v10
	v_exp_f32_e32 v26, v26
	s_waitcnt lgkmcnt(7)
	v_mfma_f32_32x32x16_bf16 v[98:113], v[2:5], v[146:149], v[98:113]
	v_add_f32_e32 v3, v26, v10
	v_sub_f32_e32 v2, v11, v217
	v_exp_f32_e32 v50, v2
	v_sub_f32_e32 v2, v27, v217
	v_exp_f32_e32 v2, v2
	s_waitcnt lgkmcnt(6)
	v_mfma_f32_32x32x16_bf16 v[98:113], v[18:21], v[130:133], v[98:113]
	v_cvt_pk_bf16_f32 v231, v10, v50
	v_add_f32_e64 v4, v2, v50
	v_add_f32_e64 v5, v3, v51
	v_add_f32_e32 v5, v4, v5
	v_cvt_pk_bf16_f32 v232, v26, v2
	v_sub_f32_e32 v2, v12, v217
	v_exp_f32_e32 v12, v2
	v_sub_f32_e32 v2, v28, v217
	v_exp_f32_e32 v18, v2
	s_waitcnt lgkmcnt(5)
	v_mfma_f32_32x32x16_bf16 v[98:113], v[34:37], v[154:157], v[98:113]
	v_add_f32_e32 v3, v18, v12
	v_sub_f32_e32 v2, v13, v217
	v_exp_f32_e32 v4, v2
	v_sub_f32_e32 v2, v29, v217
	v_exp_f32_e32 v2, v2
	s_waitcnt lgkmcnt(4)
	v_mfma_f32_32x32x16_bf16 v[98:113], v[38:41], v[134:137], v[98:113]
	v_cvt_pk_bf16_f32 v233, v12, v4
	v_add_f32_e64 v10, v2, v4
	v_add_f32_e64 v11, v3, v5
	v_add_f32_e32 v11, v10, v11
	v_cvt_pk_bf16_f32 v234, v18, v2
	v_sub_f32_e32 v2, v14, v217
	v_exp_f32_e32 v12, v2
	v_sub_f32_e32 v2, v30, v217
	v_exp_f32_e32 v13, v2
	s_waitcnt lgkmcnt(3)
	v_mfma_f32_32x32x16_bf16 v[114:129], v[6:9], v[146:149], v[114:129]
	v_add_f32_e32 v3, v13, v12
	v_sub_f32_e32 v2, v15, v217
	v_exp_f32_e32 v10, v2
	v_sub_f32_e32 v2, v31, v217
	v_exp_f32_e32 v2, v2
	s_waitcnt lgkmcnt(2)
	v_mfma_f32_32x32x16_bf16 v[114:129], v[22:25], v[130:133], v[114:129]
	v_cvt_pk_bf16_f32 v132, v12, v10
	v_add_f32_e64 v4, v2, v10
	v_add_f32_e64 v5, v3, v11
	v_add_f32_e32 v5, v4, v5
	v_cvt_pk_bf16_f32 v235, v13, v2
	v_sub_f32_e32 v2, v16, v217
	v_exp_f32_e32 v8, v2
	v_sub_f32_e32 v2, v32, v217
	v_exp_f32_e32 v9, v2
	s_waitcnt lgkmcnt(1)
	v_mfma_f32_32x32x16_bf16 v[114:129], v[42:45], v[154:157], v[114:129]
	v_add_f32_e32 v3, v9, v8
	v_sub_f32_e32 v2, v17, v217
	v_exp_f32_e32 v4, v2
	v_sub_f32_e32 v2, v33, v217
	v_exp_f32_e32 v2, v2
	s_waitcnt lgkmcnt(0)
	v_mfma_f32_32x32x16_bf16 v[114:129], v[46:49], v[134:137], v[114:129]
	v_cvt_pk_bf16_f32 v133, v8, v4
	v_add_f32_e64 v6, v2, v4
	v_add_f32_e64 v7, v3, v5
	v_add_f32_e32 v130, v6, v7
	v_cvt_pk_bf16_f32 v137, v9, v2
	v_exp_f32_e32 v198, v218
	s_nop 5
	v_mov_b64_e32 v[50:51], v[114:115]
	v_mov_b64_e32 v[34:35], v[98:99]
	v_mov_b64_e32 v[18:19], v[82:83]
	v_fmac_f32_e32 v130, v187, v198
	v_mov_b64_e32 v[2:3], v[66:67]
	v_mov_b64_e32 v[52:53], v[116:117]
	v_mov_b64_e32 v[54:55], v[118:119]
	v_mov_b64_e32 v[56:57], v[120:121]
	v_mov_b64_e32 v[58:59], v[122:123]
	v_mov_b64_e32 v[60:61], v[124:125]
	v_mov_b64_e32 v[62:63], v[126:127]
	v_mov_b64_e32 v[64:65], v[128:129]
	v_mov_b64_e32 v[36:37], v[100:101]
	v_mov_b64_e32 v[38:39], v[102:103]
	v_mov_b64_e32 v[40:41], v[104:105]
	v_mov_b64_e32 v[42:43], v[106:107]
	v_mov_b64_e32 v[44:45], v[108:109]
	v_mov_b64_e32 v[46:47], v[110:111]
	v_mov_b64_e32 v[48:49], v[112:113]
	v_mov_b64_e32 v[20:21], v[84:85]
	v_mov_b64_e32 v[22:23], v[86:87]
	v_mov_b64_e32 v[24:25], v[88:89]
	v_mov_b64_e32 v[26:27], v[90:91]
	v_mov_b64_e32 v[28:29], v[92:93]
	v_mov_b64_e32 v[30:31], v[94:95]
	v_mov_b64_e32 v[32:33], v[96:97]
	v_mov_b64_e32 v[4:5], v[68:69]
	v_mov_b64_e32 v[6:7], v[70:71]
	v_mov_b64_e32 v[8:9], v[72:73]
	v_mov_b64_e32 v[10:11], v[74:75]
	v_mov_b64_e32 v[12:13], v[76:77]
	v_mov_b64_e32 v[14:15], v[78:79]
	v_mov_b64_e32 v[16:17], v[80:81]
	v_mov_b32_e32 v216, v217
	v_mov_b32_e32 v187, v130
	v_mov_b32_e32 v146, v0
	v_mov_b32_e32 v147, v220
	v_mov_b32_e32 v148, v222
	v_mov_b32_e32 v149, v224
	v_mov_b32_e32 v130, v231
	v_mov_b32_e32 v131, v233
	v_mov_b32_e32 v154, v219
	v_mov_b32_e32 v155, v221
	v_mov_b32_e32 v156, v223
	v_mov_b32_e32 v157, v230
	v_mov_b32_e32 v134, v232
	v_mov_b32_e32 v135, v234
	v_mov_b32_e32 v136, v235
	s_andn2_b64 vcc, exec, s[26:27]
	s_cbranch_vccz .LBB0_853
	s_branch .LBB0_854
